# attnA softmax+PV blocks rescheduled by hand: V-fragment ds_reads issued 4-5 fragments ahead into freed score registers, counted lgkmcnt, exp/add/cvt spread under the MFMAs; index top-k count via per-l
# speedup vs baseline: 1.0248x; 1.0248x over previous
.LBB0_313:
	v_lshlrev_b32_e64 v69, v68, 1
	v_or_b32_e32 v69, v69, v67
	v_mov_b32_e32 v248, 0
	v_cmp_ge_u32_e64 s[4:5], v35, v69
	v_cmp_ge_u32_e64 s[6:7], v34, v69
	v_cmp_ge_u32_e64 s[8:9], v33, v69
	v_addc_co_u32_e64 v248, s[18:19], 0, v248, s[4:5]
	v_cmp_ge_u32_e64 s[4:5], v32, v69
	v_addc_co_u32_e64 v248, s[18:19], 0, v248, s[6:7]
	v_cmp_ge_u32_e64 s[6:7], v30, v69
	v_addc_co_u32_e64 v248, s[18:19], 0, v248, s[8:9]
	v_cmp_ge_u32_e64 s[8:9], v36, v69
	v_addc_co_u32_e64 v248, s[18:19], 0, v248, s[4:5]
	v_cmp_ge_u32_e64 s[4:5], v47, v69
	v_addc_co_u32_e64 v248, s[18:19], 0, v248, s[6:7]
	v_cmp_ge_u32_e64 s[6:7], v46, v69
	v_addc_co_u32_e64 v248, s[18:19], 0, v248, s[8:9]
	v_cmp_ge_u32_e64 s[8:9], v45, v69
	v_addc_co_u32_e64 v248, s[18:19], 0, v248, s[4:5]
	v_cmp_ge_u32_e64 s[4:5], v44, v69
	v_addc_co_u32_e64 v248, s[18:19], 0, v248, s[6:7]
	v_cmp_ge_u32_e64 s[6:7], v43, v69
	v_addc_co_u32_e64 v248, s[18:19], 0, v248, s[8:9]
	v_cmp_ge_u32_e64 s[8:9], v41, v69
	v_addc_co_u32_e64 v248, s[18:19], 0, v248, s[4:5]
	v_cmp_ge_u32_e64 s[4:5], v40, v69
	v_addc_co_u32_e64 v248, s[18:19], 0, v248, s[6:7]
	v_cmp_ge_u32_e64 s[6:7], v42, v69
	v_addc_co_u32_e64 v248, s[18:19], 0, v248, s[8:9]
	v_cmp_ge_u32_e64 s[8:9], v39, v69
	v_addc_co_u32_e64 v248, s[18:19], 0, v248, s[4:5]
	v_cmp_ge_u32_e64 s[4:5], v38, v69
	v_addc_co_u32_e64 v248, s[18:19], 0, v248, s[6:7]
	v_cmp_ge_u32_e64 s[6:7], v37, v69
	v_addc_co_u32_e64 v248, s[18:19], 0, v248, s[8:9]
	v_cmp_ge_u32_e64 s[8:9], v48, v69
	v_addc_co_u32_e64 v248, s[18:19], 0, v248, s[4:5]
	v_cmp_ge_u32_e64 s[4:5], v63, v69
	v_addc_co_u32_e64 v248, s[18:19], 0, v248, s[6:7]
	v_cmp_ge_u32_e64 s[6:7], v61, v69
	v_addc_co_u32_e64 v248, s[18:19], 0, v248, s[8:9]
	v_cmp_ge_u32_e64 s[8:9], v59, v69
	v_addc_co_u32_e64 v248, s[18:19], 0, v248, s[4:5]
	v_cmp_ge_u32_e64 s[4:5], v57, v69
	v_addc_co_u32_e64 v248, s[18:19], 0, v248, s[6:7]
	v_cmp_ge_u32_e64 s[6:7], v55, v69
	v_addc_co_u32_e64 v248, s[18:19], 0, v248, s[8:9]
	v_cmp_ge_u32_e64 s[8:9], v54, v69
	v_addc_co_u32_e64 v248, s[18:19], 0, v248, s[4:5]
	v_cmp_ge_u32_e64 s[4:5], v52, v69
	v_addc_co_u32_e64 v248, s[18:19], 0, v248, s[6:7]
	v_cmp_ge_u32_e64 s[6:7], v62, v69
	v_addc_co_u32_e64 v248, s[18:19], 0, v248, s[8:9]
	v_cmp_ge_u32_e64 s[8:9], v60, v69
	v_addc_co_u32_e64 v248, s[18:19], 0, v248, s[4:5]
	v_cmp_ge_u32_e64 s[4:5], v58, v69
	v_addc_co_u32_e64 v248, s[18:19], 0, v248, s[6:7]
	v_cmp_ge_u32_e64 s[6:7], v56, v69
	v_addc_co_u32_e64 v248, s[18:19], 0, v248, s[8:9]
	v_cmp_ge_u32_e64 s[8:9], v53, v69
	v_addc_co_u32_e64 v248, s[18:19], 0, v248, s[4:5]
	v_cmp_ge_u32_e64 s[4:5], v51, v69
	v_addc_co_u32_e64 v248, s[18:19], 0, v248, s[6:7]
	v_cmp_ge_u32_e64 s[6:7], v50, v69
	v_addc_co_u32_e64 v248, s[18:19], 0, v248, s[8:9]
	v_cmp_ge_u32_e64 s[8:9], v49, v69
	v_addc_co_u32_e64 v248, s[18:19], 0, v248, s[4:5]
	v_cmp_ge_u32_e64 s[4:5], v64, v69
	v_addc_co_u32_e64 v248, s[18:19], 0, v248, s[6:7]
	v_cmp_ge_u32_e64 s[6:7], v66, v69
	v_addc_co_u32_e64 v248, s[18:19], 0, v248, s[8:9]
	v_cmp_ge_u32_e64 s[8:9], v19, v69
	v_addc_co_u32_e64 v248, s[18:19], 0, v248, s[4:5]
	v_cmp_ge_u32_e64 s[4:5], v16, v69
	v_addc_co_u32_e64 v248, s[18:19], 0, v248, s[6:7]
	v_cmp_ge_u32_e64 s[6:7], v11, v69
	v_addc_co_u32_e64 v248, s[18:19], 0, v248, s[8:9]
	v_cmp_ge_u32_e64 s[8:9], v8, v69
	v_addc_co_u32_e64 v248, s[18:19], 0, v248, s[4:5]
	v_cmp_ge_u32_e64 s[4:5], v7, v69
	v_addc_co_u32_e64 v248, s[18:19], 0, v248, s[6:7]
	v_cmp_ge_u32_e64 s[6:7], v4, v69
	v_addc_co_u32_e64 v248, s[18:19], 0, v248, s[8:9]
	v_cmp_ge_u32_e64 s[8:9], v23, v69
	v_addc_co_u32_e64 v248, s[18:19], 0, v248, s[4:5]
	v_cmp_ge_u32_e64 s[4:5], v20, v69
	v_addc_co_u32_e64 v248, s[18:19], 0, v248, s[6:7]
	v_cmp_ge_u32_e64 s[6:7], v13, v69
	v_addc_co_u32_e64 v248, s[18:19], 0, v248, s[8:9]
	v_cmp_ge_u32_e64 s[8:9], v10, v69
	v_addc_co_u32_e64 v248, s[18:19], 0, v248, s[4:5]
	v_cmp_ge_u32_e64 s[4:5], v9, v69
	v_addc_co_u32_e64 v248, s[18:19], 0, v248, s[6:7]
	v_cmp_ge_u32_e64 s[6:7], v6, v69
	v_addc_co_u32_e64 v248, s[18:19], 0, v248, s[8:9]
	v_cmp_ge_u32_e64 s[8:9], v5, v69
	v_addc_co_u32_e64 v248, s[18:19], 0, v248, s[4:5]
	v_cmp_ge_u32_e64 s[4:5], v0, v69
	v_addc_co_u32_e64 v248, s[18:19], 0, v248, s[6:7]
	v_cmp_ge_u32_e64 s[6:7], v65, v69
	v_addc_co_u32_e64 v248, s[18:19], 0, v248, s[8:9]
	v_cmp_ge_u32_e64 s[8:9], v25, v69
	v_addc_co_u32_e64 v248, s[18:19], 0, v248, s[4:5]
	v_cmp_ge_u32_e64 s[4:5], v22, v69
	v_addc_co_u32_e64 v248, s[18:19], 0, v248, s[6:7]
	v_cmp_ge_u32_e64 s[6:7], v21, v69
	v_addc_co_u32_e64 v248, s[18:19], 0, v248, s[8:9]
	v_cmp_ge_u32_e64 s[8:9], v18, v69
	v_addc_co_u32_e64 v248, s[18:19], 0, v248, s[4:5]
	v_cmp_ge_u32_e64 s[4:5], v15, v69
	v_addc_co_u32_e64 v248, s[18:19], 0, v248, s[6:7]
	v_cmp_ge_u32_e64 s[6:7], v12, v69
	v_addc_co_u32_e64 v248, s[18:19], 0, v248, s[8:9]
	v_cmp_ge_u32_e64 s[8:9], v17, v69
	v_addc_co_u32_e64 v248, s[18:19], 0, v248, s[4:5]
	v_cmp_ge_u32_e64 s[4:5], v14, v69
	v_addc_co_u32_e64 v248, s[18:19], 0, v248, s[6:7]
	v_cmp_ge_u32_e64 s[6:7], v31, v69
	v_addc_co_u32_e64 v248, s[18:19], 0, v248, s[8:9]
	v_cmp_ge_u32_e64 s[8:9], v28, v69
	v_addc_co_u32_e64 v248, s[18:19], 0, v248, s[4:5]
	v_cmp_ge_u32_e64 s[4:5], v29, v69
	v_addc_co_u32_e64 v248, s[18:19], 0, v248, s[6:7]
	v_cmp_ge_u32_e64 s[6:7], v26, v69
	v_addc_co_u32_e64 v248, s[18:19], 0, v248, s[8:9]
	v_cmp_ge_u32_e64 s[8:9], v27, v69
	v_addc_co_u32_e64 v248, s[18:19], 0, v248, s[4:5]
	v_cmp_ge_u32_e64 s[4:5], v24, v69
	v_addc_co_u32_e64 v248, s[18:19], 0, v248, s[6:7]
	v_addc_co_u32_e64 v248, s[18:19], 0, v248, s[8:9]
	v_addc_co_u32_e64 v248, s[18:19], 0, v248, s[4:5]
	s_nop 1
	v_add_u32_dpp v248, v248, v248 quad_perm:[1,0,3,2] row_mask:0xf bank_mask:0xf
	s_nop 1
	v_add_u32_dpp v248, v248, v248 quad_perm:[2,3,0,1] row_mask:0xf bank_mask:0xf
	s_nop 1
	v_add_u32_dpp v248, v248, v248 row_half_mirror row_mask:0xf bank_mask:0xf
	s_nop 1
	v_add_u32_dpp v248, v248, v248 row_mirror row_mask:0xf bank_mask:0xf
	s_nop 1
	v_add_u32_dpp v248, v248, v248 row_bcast:15 row_mask:0xa bank_mask:0xf
	s_nop 1
	v_add_u32_dpp v248, v248, v248 row_bcast:31 row_mask:0xc bank_mask:0xf
	s_nop 1
	v_readlane_b32 s2, v248, 63
	s_cmpk_gt_i32 s2, 0xff
	s_cselect_b64 vcc, -1, 0
	s_cmpk_lg_i32 s2, 0x100
	s_cselect_b64 s[0:1], -1, 0
	s_cmpk_eq_i32 s2, 0x100
	v_cndmask_b32_e32 v67, v67, v69, vcc
	s_cselect_b64 s[2:3], -1, 0
	v_subrev_co_u32_e32 v68, vcc, 1, v68
	s_or_b64 s[2:3], s[2:3], vcc
	s_andn2_b64 vcc, exec, s[2:3]
	s_cbranch_vccnz .LBB0_313
	s_andn2_b64 vcc, exec, s[0:1]
	s_cbranch_vccnz .LBB0_448
	v_cmp_gt_u32_e64 s[40:41], v35, v67
	v_cmp_gt_u32_e64 s[42:43], v34, v67
	s_bcnt1_i32_b64 s44, s[40:41]
	s_bcnt1_i32_b64 s45, s[42:43]
	v_cmp_gt_u32_e64 s[38:39], v33, v67
	s_bcnt1_i32_b64 s48, s[38:39]
	v_cmp_gt_u32_e64 s[36:37], v32, v67
	s_add_i32 s44, s44, s45
	s_bcnt1_i32_b64 s49, s[36:37]
	v_cmp_gt_u32_e64 s[34:35], v30, v67
	s_add_i32 s44, s44, s48
	s_bcnt1_i32_b64 s50, s[34:35]
	v_cmp_gt_u32_e64 s[30:31], v36, v67
	s_add_i32 s44, s44, s49
	s_bcnt1_i32_b64 s51, s[30:31]
	v_cmp_gt_u32_e64 s[28:29], v47, v67
	s_add_i32 s44, s44, s50
	s_bcnt1_i32_b64 s52, s[28:29]
	v_cmp_gt_u32_e64 s[26:27], v46, v67
	s_add_i32 s44, s44, s51
	s_bcnt1_i32_b64 s53, s[26:27]
	v_cmp_gt_u32_e64 s[24:25], v45, v67
	s_add_i32 s44, s44, s52
	s_bcnt1_i32_b64 s54, s[24:25]
	v_cmp_gt_u32_e64 s[22:23], v44, v67
	s_add_i32 s44, s44, s53
	s_bcnt1_i32_b64 s55, s[22:23]
	v_cmp_gt_u32_e64 s[20:21], v43, v67
	s_add_i32 s44, s44, s54
	s_bcnt1_i32_b64 s56, s[20:21]
	v_cmp_gt_u32_e64 s[18:19], v41, v67
	s_add_i32 s44, s44, s55
	s_bcnt1_i32_b64 s57, s[18:19]
	v_cmp_gt_u32_e64 s[16:17], v40, v67
	s_add_i32 s44, s44, s56
	s_bcnt1_i32_b64 s58, s[16:17]
	v_cmp_gt_u32_e64 s[14:15], v42, v67
	s_add_i32 s44, s44, s57
	s_bcnt1_i32_b64 s59, s[14:15]
	v_cmp_gt_u32_e64 s[12:13], v39, v67
	s_add_i32 s44, s44, s58
	s_bcnt1_i32_b64 s62, s[12:13]
	v_cmp_gt_u32_e64 s[2:3], v38, v67
	s_add_i32 s44, s44, s59
	s_bcnt1_i32_b64 s63, s[2:3]
	v_cmp_gt_u32_e64 s[4:5], v37, v67
	s_add_i32 s44, s44, s62
	s_bcnt1_i32_b64 s64, s[4:5]
	v_cmp_gt_u32_e64 s[10:11], v48, v67
	s_add_i32 s44, s44, s63
	s_bcnt1_i32_b64 s65, s[10:11]
	v_cmp_gt_u32_e64 s[8:9], v63, v67
	s_add_i32 s44, s44, s64
	s_bcnt1_i32_b64 s68, s[8:9]
	v_cmp_gt_u32_e64 s[6:7], v61, v67
	s_add_i32 s44, s44, s65
	s_bcnt1_i32_b64 s69, s[6:7]
	v_cmp_gt_u32_e64 s[0:1], v59, v67
	s_add_i32 s44, s44, s68
	s_bcnt1_i32_b64 vcc_lo, s[0:1]
	v_cmp_gt_u32_e64 s[96:97], v57, v67
	s_add_i32 s44, s44, s69
	s_bcnt1_i32_b64 vcc_hi, s[96:97]
	v_cmp_gt_u32_e64 s[46:47], v55, v67
	s_add_i32 s44, s44, vcc_lo
	s_bcnt1_i32_b64 s60, s[46:47]
	v_cmp_gt_u32_e64 s[92:93], v54, v67
	s_add_i32 s44, s44, vcc_hi
	s_bcnt1_i32_b64 s61, s[92:93]
	v_cmp_gt_u32_e64 s[90:91], v52, v67
	s_add_i32 s44, s44, s60
	s_bcnt1_i32_b64 s66, s[90:91]
	v_cmp_gt_u32_e64 s[88:89], v62, v67
	s_add_i32 s44, s44, s61
	s_bcnt1_i32_b64 s67, s[88:89]
	v_cmp_gt_u32_e64 s[86:87], v60, v67
	s_add_i32 s44, s44, s66
	s_bcnt1_i32_b64 s70, s[86:87]
	v_cmp_gt_u32_e64 s[84:85], v58, v67
	v_cmp_gt_u32_e64 s[74:75], v53, v67
	s_add_i32 s44, s44, s67
	s_bcnt1_i32_b64 s71, s[84:85]
	v_cmp_gt_u32_e64 s[80:81], v56, v67
	v_writelane_b32 v255, s74, 11
	s_add_i32 s44, s44, s70
	s_bcnt1_i32_b64 s72, s[80:81]
	v_writelane_b32 v255, s75, 12
	s_bcnt1_i32_b64 s73, s[74:75]
	v_cmp_gt_u32_e64 s[74:75], v51, v67
	s_add_i32 s44, s44, s71
	s_add_i32 s44, s44, s72
	v_writelane_b32 v255, s74, 13
	v_cmp_gt_u32_e64 s[82:83], v50, v67
	s_add_i32 s44, s44, s73
	v_writelane_b32 v255, s75, 14
	s_bcnt1_i32_b64 s74, s[74:75]
	s_bcnt1_i32_b64 s45, s[82:83]
	v_cmp_gt_u32_e64 s[78:79], v49, v67
	s_add_i32 s44, s44, s74
	v_cmp_gt_u32_e64 s[76:77], v64, v67
	s_bcnt1_i32_b64 s48, s[78:79]
	s_add_i32 s44, s44, s45
	v_writelane_b32 v255, s76, 15
	s_bcnt1_i32_b64 s49, s[76:77]
	v_cmp_gt_u32_e64 s[54:55], v66, v67
	s_add_i32 s44, s44, s48
	s_bcnt1_i32_b64 s50, s[54:55]
	v_cmp_gt_u32_e64 s[56:57], v19, v67
	s_add_i32 s44, s44, s49
	v_writelane_b32 v255, s77, 16
	v_cmp_gt_u32_e64 s[76:77], v16, v67
	s_bcnt1_i32_b64 s51, s[56:57]
	s_add_i32 s44, s44, s50
	s_bcnt1_i32_b64 s52, s[76:77]
	v_cmp_gt_u32_e64 s[68:69], v11, v67
	s_add_i32 s44, s44, s51
	v_cmp_gt_u32_e64 s[64:65], v8, v67
	s_bcnt1_i32_b64 s53, s[68:69]
	s_add_i32 s44, s44, s52
	s_bcnt1_i32_b64 s75, s[64:65]
	v_cmp_gt_u32_e64 s[62:63], v7, v67
	s_add_i32 s44, s44, s53
	v_cmp_gt_u32_e64 s[52:53], v13, v67
	v_cmp_gt_u32_e64 s[58:59], v4, v67
	s_bcnt1_i32_b64 s70, s[62:63]
	s_add_i32 s44, s44, s75
	v_writelane_b32 v255, s52, 17
	s_bcnt1_i32_b64 s71, s[58:59]
	v_cmp_gt_u32_e64 s[66:67], v23, v67
	v_cmp_gt_u32_e64 s[50:51], v10, v67
	s_add_i32 s44, s44, s70
	v_writelane_b32 v255, s53, 18
	v_cmp_gt_u32_e64 s[60:61], v20, v67
	s_bcnt1_i32_b64 s45, s[66:67]
	s_add_i32 s44, s44, s71
	v_writelane_b32 v255, s50, 19
	s_bcnt1_i32_b64 s48, s[60:61]
	s_bcnt1_i32_b64 s49, s[52:53]
	v_writelane_b32 v255, s51, 20
	s_add_i32 s44, s44, s45
	v_cmp_gt_u32_e64 s[52:53], v9, v67
	s_add_i32 s44, s44, s48
	s_bcnt1_i32_b64 s50, s[50:51]
	v_writelane_b32 v255, s52, 21
	s_add_i32 s44, s44, s49
	v_cmp_gt_u32_e64 s[48:49], v6, v67
	v_writelane_b32 v255, s53, 22
	s_bcnt1_i32_b64 s45, s[52:53]
	s_add_i32 s44, s44, s50
	v_writelane_b32 v255, s48, 23
	s_add_i32 s44, s44, s45
	s_bcnt1_i32_b64 s45, s[48:49]
	v_writelane_b32 v255, s49, 24
	v_cmp_gt_u32_e64 s[48:49], v5, v67
	s_add_i32 s44, s44, s45
	v_readlane_b32 s74, v254, 56
	v_writelane_b32 v255, s48, 25
	s_bcnt1_i32_b64 s45, s[48:49]
	s_add_i32 s44, s44, s45
	v_writelane_b32 v255, s49, 26
	v_cmp_gt_u32_e64 s[48:49], v0, v67
	v_readlane_b32 s75, v254, 57
	v_cmp_gt_u32_e64 s[72:73], v27, v67
	v_writelane_b32 v255, s48, 27
	s_bcnt1_i32_b64 s45, s[48:49]
	s_add_i32 s44, s44, s45
	v_writelane_b32 v255, s49, 28
	v_cmp_gt_u32_e64 s[48:49], v65, v67
	v_cmp_gt_u32_e64 s[70:71], v24, v67
	v_cmp_eq_u32_e32 vcc, v35, v67
	v_writelane_b32 v255, s48, 29
	s_bcnt1_i32_b64 s45, s[48:49]
	s_add_i32 s44, s44, s45
	v_writelane_b32 v255, s49, 30
	v_cmp_gt_u32_e64 s[48:49], v25, v67
	v_and_b32_e32 v69, vcc_lo, v178
	v_and_b32_e32 v68, vcc_hi, v179
	v_writelane_b32 v255, s48, 31
	s_bcnt1_i32_b64 s45, s[48:49]
	s_add_i32 s44, s44, s45
	v_writelane_b32 v255, s49, 32
	v_cmp_gt_u32_e64 s[48:49], v22, v67
	v_bcnt_u32_b32 v69, v69, 0
	v_bcnt_u32_b32 v68, v68, v69
	v_writelane_b32 v255, s48, 33
	s_bcnt1_i32_b64 s45, s[48:49]
	s_add_i32 s44, s44, s45
	v_writelane_b32 v255, s49, 34
	v_cmp_gt_u32_e64 s[48:49], v21, v67
	s_nop 1
	v_writelane_b32 v255, s48, 35
	s_bcnt1_i32_b64 s45, s[48:49]
	s_add_i32 s44, s44, s45
	v_writelane_b32 v255, s49, 36
	v_cmp_gt_u32_e64 s[48:49], v18, v67
	s_nop 1
	v_writelane_b32 v255, s48, 37
	s_bcnt1_i32_b64 s45, s[48:49]
	s_add_i32 s44, s44, s45
	v_writelane_b32 v255, s49, 38
	v_cmp_gt_u32_e64 s[48:49], v15, v67
	s_nop 1
	v_writelane_b32 v254, s48, 61
	s_bcnt1_i32_b64 s45, s[48:49]
	s_add_i32 s44, s44, s45
	v_writelane_b32 v254, s49, 62
	v_cmp_gt_u32_e64 s[48:49], v12, v67
	s_nop 1
	v_writelane_b32 v255, s48, 1
	s_bcnt1_i32_b64 s45, s[48:49]
	s_add_i32 s44, s44, s45
	v_writelane_b32 v255, s49, 2
	v_cmp_gt_u32_e64 s[48:49], v17, v67
	s_nop 1
	v_writelane_b32 v254, s48, 63
	s_bcnt1_i32_b64 s45, s[48:49]
	s_add_i32 s44, s44, s45
	v_writelane_b32 v255, s49, 0
	v_cmp_gt_u32_e64 s[48:49], v14, v67
	s_nop 1
	v_writelane_b32 v255, s48, 3
	s_bcnt1_i32_b64 s45, s[48:49]
	s_add_i32 s44, s44, s45
	v_writelane_b32 v255, s49, 4
	v_cmp_gt_u32_e64 s[48:49], v31, v67
	s_nop 1
	v_writelane_b32 v255, s48, 5
	s_bcnt1_i32_b64 s45, s[48:49]
	s_add_i32 s44, s44, s45
	v_writelane_b32 v255, s49, 6
	v_cmp_gt_u32_e64 s[48:49], v28, v67
	s_nop 1
	v_writelane_b32 v255, s48, 7
	s_bcnt1_i32_b64 s45, s[48:49]
	s_add_i32 s44, s44, s45
	v_writelane_b32 v255, s49, 8
	v_cmp_gt_u32_e64 s[48:49], v29, v67
	s_nop 1
	v_writelane_b32 v255, s48, 9
	s_bcnt1_i32_b64 s45, s[48:49]
	s_add_i32 s44, s44, s45
	v_writelane_b32 v255, s49, 10
	v_cmp_gt_u32_e64 s[48:49], v26, v67
	s_nop 1
	v_writelane_b32 v254, s48, 59
	s_bcnt1_i32_b64 s45, s[48:49]
	s_add_i32 s44, s44, s45
	s_bcnt1_i32_b64 s45, s[72:73]
	s_add_i32 s44, s44, s45
	s_bcnt1_i32_b64 s45, s[70:71]
	s_add_i32 s44, s44, s45
	s_sub_i32 s50, 0x100, s44
	v_cmp_gt_i32_e64 s[44:45], s50, v68
	s_and_b64 s[44:45], vcc, s[44:45]
	v_writelane_b32 v254, s49, 60
	v_cndmask_b32_e64 v68, 0, 1, s[44:45]
	v_cmp_ne_u32_e64 s[44:45], 0, v68
	s_and_saveexec_b64 s[48:49], s[74:75]
	s_cbranch_execz .LBB0_317
	s_or_b64 s[40:41], s[44:45], s[40:41]
	v_mov_b64_e32 v[68:69], s[40:41]
	global_store_dwordx2 v[2:3], v[68:69], off

.LBB0_515:
	v_lshlrev_b32_e64 v20, v19, 1
	v_or_b32_e32 v20, v20, v17
	v_mov_b32_e32 v248, 0
	v_cmp_ge_u32_e64 s[4:5], v35, v20
	v_cmp_ge_u32_e64 s[6:7], v34, v20
	v_cmp_ge_u32_e64 s[8:9], v33, v20
	v_addc_co_u32_e64 v248, s[18:19], 0, v248, s[4:5]
	v_cmp_ge_u32_e64 s[4:5], v32, v20
	v_addc_co_u32_e64 v248, s[18:19], 0, v248, s[6:7]
	v_cmp_ge_u32_e64 s[6:7], v30, v20
	v_addc_co_u32_e64 v248, s[18:19], 0, v248, s[8:9]
	v_cmp_ge_u32_e64 s[8:9], v36, v20
	v_addc_co_u32_e64 v248, s[18:19], 0, v248, s[4:5]
	v_cmp_ge_u32_e64 s[4:5], v47, v20
	v_addc_co_u32_e64 v248, s[18:19], 0, v248, s[6:7]
	v_cmp_ge_u32_e64 s[6:7], v46, v20
	v_addc_co_u32_e64 v248, s[18:19], 0, v248, s[8:9]
	v_cmp_ge_u32_e64 s[8:9], v45, v20
	v_addc_co_u32_e64 v248, s[18:19], 0, v248, s[4:5]
	v_cmp_ge_u32_e64 s[4:5], v44, v20
	v_addc_co_u32_e64 v248, s[18:19], 0, v248, s[6:7]
	v_cmp_ge_u32_e64 s[6:7], v43, v20
	v_addc_co_u32_e64 v248, s[18:19], 0, v248, s[8:9]
	v_cmp_ge_u32_e64 s[8:9], v41, v20
	v_addc_co_u32_e64 v248, s[18:19], 0, v248, s[4:5]
	v_cmp_ge_u32_e64 s[4:5], v40, v20
	v_addc_co_u32_e64 v248, s[18:19], 0, v248, s[6:7]
	v_cmp_ge_u32_e64 s[6:7], v42, v20
	v_addc_co_u32_e64 v248, s[18:19], 0, v248, s[8:9]
	v_cmp_ge_u32_e64 s[8:9], v39, v20
	v_addc_co_u32_e64 v248, s[18:19], 0, v248, s[4:5]
	v_cmp_ge_u32_e64 s[4:5], v38, v20
	v_addc_co_u32_e64 v248, s[18:19], 0, v248, s[6:7]
	v_cmp_ge_u32_e64 s[6:7], v37, v20
	v_addc_co_u32_e64 v248, s[18:19], 0, v248, s[8:9]
	v_cmp_ge_u32_e64 s[8:9], v48, v20
	v_addc_co_u32_e64 v248, s[18:19], 0, v248, s[4:5]
	v_cmp_ge_u32_e64 s[4:5], v63, v20
	v_addc_co_u32_e64 v248, s[18:19], 0, v248, s[6:7]
	v_cmp_ge_u32_e64 s[6:7], v61, v20
	v_addc_co_u32_e64 v248, s[18:19], 0, v248, s[8:9]
	v_cmp_ge_u32_e64 s[8:9], v59, v20
	v_addc_co_u32_e64 v248, s[18:19], 0, v248, s[4:5]
	v_cmp_ge_u32_e64 s[4:5], v57, v20
	v_addc_co_u32_e64 v248, s[18:19], 0, v248, s[6:7]
	v_cmp_ge_u32_e64 s[6:7], v55, v20
	v_addc_co_u32_e64 v248, s[18:19], 0, v248, s[8:9]
	v_cmp_ge_u32_e64 s[8:9], v54, v20
	v_addc_co_u32_e64 v248, s[18:19], 0, v248, s[4:5]
	v_cmp_ge_u32_e64 s[4:5], v52, v20
	v_addc_co_u32_e64 v248, s[18:19], 0, v248, s[6:7]
	v_cmp_ge_u32_e64 s[6:7], v62, v20
	v_addc_co_u32_e64 v248, s[18:19], 0, v248, s[8:9]
	v_cmp_ge_u32_e64 s[8:9], v60, v20
	v_addc_co_u32_e64 v248, s[18:19], 0, v248, s[4:5]
	v_cmp_ge_u32_e64 s[4:5], v58, v20
	v_addc_co_u32_e64 v248, s[18:19], 0, v248, s[6:7]
	v_cmp_ge_u32_e64 s[6:7], v56, v20
	v_addc_co_u32_e64 v248, s[18:19], 0, v248, s[8:9]
	v_cmp_ge_u32_e64 s[8:9], v53, v20
	v_addc_co_u32_e64 v248, s[18:19], 0, v248, s[4:5]
	v_cmp_ge_u32_e64 s[4:5], v51, v20
	v_addc_co_u32_e64 v248, s[18:19], 0, v248, s[6:7]
	v_cmp_ge_u32_e64 s[6:7], v50, v20
	v_addc_co_u32_e64 v248, s[18:19], 0, v248, s[8:9]
	v_cmp_ge_u32_e64 s[8:9], v49, v20
	v_addc_co_u32_e64 v248, s[18:19], 0, v248, s[4:5]
	v_cmp_ge_u32_e64 s[4:5], v14, v20
	v_addc_co_u32_e64 v248, s[18:19], 0, v248, s[6:7]
	v_cmp_ge_u32_e64 s[6:7], v18, v20
	v_addc_co_u32_e64 v248, s[18:19], 0, v248, s[8:9]
	v_cmp_ge_u32_e64 s[8:9], v9, v20
	v_addc_co_u32_e64 v248, s[18:19], 0, v248, s[4:5]
	v_cmp_ge_u32_e64 s[4:5], v6, v20
	v_addc_co_u32_e64 v248, s[18:19], 0, v248, s[6:7]
	v_cmp_ge_u32_e64 s[6:7], v7, v20
	v_addc_co_u32_e64 v248, s[18:19], 0, v248, s[8:9]
	v_cmp_ge_u32_e64 s[8:9], v4, v20
	v_addc_co_u32_e64 v248, s[18:19], 0, v248, s[4:5]
	v_cmp_ge_u32_e64 s[4:5], v5, v20
	v_addc_co_u32_e64 v248, s[18:19], 0, v248, s[6:7]
	v_cmp_ge_u32_e64 s[6:7], v0, v20
	v_addc_co_u32_e64 v248, s[18:19], 0, v248, s[8:9]
	v_cmp_ge_u32_e64 s[8:9], v15, v20
	v_addc_co_u32_e64 v248, s[18:19], 0, v248, s[4:5]
	v_cmp_ge_u32_e64 s[4:5], v12, v20
	v_addc_co_u32_e64 v248, s[18:19], 0, v248, s[6:7]
	v_cmp_ge_u32_e64 s[6:7], v13, v20
	v_addc_co_u32_e64 v248, s[18:19], 0, v248, s[8:9]
	v_cmp_ge_u32_e64 s[8:9], v10, v20
	v_addc_co_u32_e64 v248, s[18:19], 0, v248, s[4:5]
	v_cmp_ge_u32_e64 s[4:5], v11, v20
	v_addc_co_u32_e64 v248, s[18:19], 0, v248, s[6:7]
	v_cmp_ge_u32_e64 s[6:7], v8, v20
	v_addc_co_u32_e64 v248, s[18:19], 0, v248, s[8:9]
	v_cmp_ge_u32_e64 s[8:9], v16, v20
	v_addc_co_u32_e64 v248, s[18:19], 0, v248, s[4:5]
	v_addc_co_u32_e64 v248, s[18:19], 0, v248, s[6:7]
	v_addc_co_u32_e64 v248, s[18:19], 0, v248, s[8:9]
	s_nop 1
	v_add_u32_dpp v248, v248, v248 quad_perm:[1,0,3,2] row_mask:0xf bank_mask:0xf
	s_nop 1
	v_add_u32_dpp v248, v248, v248 quad_perm:[2,3,0,1] row_mask:0xf bank_mask:0xf
	s_nop 1
	v_add_u32_dpp v248, v248, v248 row_half_mirror row_mask:0xf bank_mask:0xf
	s_nop 1
	v_add_u32_dpp v248, v248, v248 row_mirror row_mask:0xf bank_mask:0xf
	s_nop 1
	v_add_u32_dpp v248, v248, v248 row_bcast:15 row_mask:0xa bank_mask:0xf
	s_nop 1
	v_add_u32_dpp v248, v248, v248 row_bcast:31 row_mask:0xc bank_mask:0xf
	s_nop 1
	v_readlane_b32 s2, v248, 63
	s_cmpk_gt_u32 s2, 0xff
	s_cselect_b64 vcc, -1, 0
	s_cmpk_lg_i32 s2, 0x100
	s_cselect_b64 s[0:1], -1, 0
	s_cmpk_eq_i32 s2, 0x100
	v_cndmask_b32_e32 v17, v17, v20, vcc
	s_cselect_b64 s[2:3], -1, 0
	v_subrev_co_u32_e32 v19, vcc, 1, v19
	s_or_b64 s[2:3], s[2:3], vcc
	s_andn2_b64 vcc, exec, s[2:3]
	s_cbranch_vccnz .LBB0_515
	s_andn2_b64 vcc, exec, s[0:1]
	s_mov_b64 s[0:1], -1
	s_cbranch_vccnz .LBB0_676
	v_cmp_gt_u32_e64 s[12:13], v35, v17
	v_cmp_gt_u32_e64 s[92:93], v34, v17
	s_bcnt1_i32_b64 s14, s[12:13]
	s_bcnt1_i32_b64 s15, s[92:93]
	v_cmp_gt_u32_e64 s[90:91], v33, v17
	s_bcnt1_i32_b64 s16, s[90:91]
	v_cmp_gt_u32_e64 s[88:89], v32, v17
	s_add_i32 s14, s14, s15
	s_bcnt1_i32_b64 s17, s[88:89]
	v_cmp_gt_u32_e64 s[86:87], v30, v17
	s_add_i32 s14, s14, s16
	s_bcnt1_i32_b64 s18, s[86:87]
	v_cmp_gt_u32_e64 s[84:85], v36, v17
	s_add_i32 s14, s14, s17
	s_bcnt1_i32_b64 s19, s[84:85]
	v_cmp_gt_u32_e64 s[82:83], v47, v17
	s_add_i32 s14, s14, s18
	s_bcnt1_i32_b64 s20, s[82:83]
	v_cmp_gt_u32_e64 s[80:81], v46, v17
	s_add_i32 s14, s14, s19
	s_bcnt1_i32_b64 s21, s[80:81]
	v_cmp_gt_u32_e64 s[78:79], v45, v17
	s_add_i32 s14, s14, s20
	s_bcnt1_i32_b64 s22, s[78:79]
	v_cmp_gt_u32_e64 s[76:77], v44, v17
	s_add_i32 s14, s14, s21
	s_bcnt1_i32_b64 s23, s[76:77]
	v_cmp_gt_u32_e64 s[44:45], v43, v17
	s_add_i32 s14, s14, s22
	s_bcnt1_i32_b64 s24, s[44:45]
	v_cmp_gt_u32_e64 s[72:73], v41, v17
	s_add_i32 s14, s14, s23
	s_bcnt1_i32_b64 s25, s[72:73]
	v_cmp_gt_u32_e64 s[70:71], v40, v17
	s_add_i32 s14, s14, s24
	s_bcnt1_i32_b64 s26, s[70:71]
	v_cmp_gt_u32_e64 s[68:69], v42, v17
	s_add_i32 s14, s14, s25
	s_bcnt1_i32_b64 s27, s[68:69]
	v_cmp_gt_u32_e64 s[66:67], v39, v17
	s_add_i32 s14, s14, s26
	s_bcnt1_i32_b64 s28, s[66:67]
	v_cmp_gt_u32_e64 s[64:65], v38, v17
	s_add_i32 s14, s14, s27
	s_bcnt1_i32_b64 s29, s[64:65]
	v_cmp_gt_u32_e64 s[62:63], v37, v17
	s_add_i32 s14, s14, s28
	v_cmp_gt_u32_e64 s[4:5], v48, v17
	s_bcnt1_i32_b64 s30, s[62:63]
	s_add_i32 s14, s14, s29
	s_bcnt1_i32_b64 s31, s[4:5]
	v_cmp_gt_u32_e64 s[60:61], v63, v17
	s_add_i32 s14, s14, s30
	s_bcnt1_i32_b64 s96, s[60:61]
	v_cmp_gt_u32_e64 s[10:11], v61, v17
	s_add_i32 s14, s14, s31
	v_cmp_gt_u32_e64 s[8:9], v59, v17
	s_bcnt1_i32_b64 s97, s[10:11]
	s_add_i32 s14, s14, s96
	s_bcnt1_i32_b64 vcc_lo, s[8:9]
	v_cmp_gt_u32_e64 s[6:7], v57, v17
	s_add_i32 s14, s14, s97
	v_cmp_gt_u32_e64 s[0:1], v55, v17
	s_bcnt1_i32_b64 vcc_hi, s[6:7]
	s_add_i32 s14, s14, vcc_lo
	s_bcnt1_i32_b64 s34, s[0:1]
	v_cmp_gt_u32_e64 s[2:3], v54, v17
	s_add_i32 s14, s14, vcc_hi
	v_cmp_gt_u32_e64 s[58:59], v52, v17
	s_bcnt1_i32_b64 s35, s[2:3]
	s_add_i32 s14, s14, s34
	s_bcnt1_i32_b64 s36, s[58:59]
	v_cmp_gt_u32_e64 s[56:57], v62, v17
	s_add_i32 s14, s14, s35
	v_cmp_gt_u32_e64 s[54:55], v60, v17
	s_bcnt1_i32_b64 s37, s[56:57]
	v_cmp_gt_u32_e64 s[46:47], v53, v17
	s_add_i32 s14, s14, s36
	s_bcnt1_i32_b64 s38, s[54:55]
	v_cmp_gt_u32_e64 s[52:53], v58, v17
	v_writelane_b32 v254, s46, 61
	s_add_i32 s14, s14, s37
	v_cmp_gt_u32_e64 s[50:51], v56, v17
	s_bcnt1_i32_b64 s39, s[52:53]
	v_cmp_gt_u32_e64 s[42:43], v51, v17
	v_writelane_b32 v254, s47, 62
	s_add_i32 s14, s14, s38
	s_bcnt1_i32_b64 s40, s[50:51]
	v_writelane_b32 v254, s42, 63
	v_cmp_gt_u32_e64 s[48:49], v50, v17
	s_add_i32 s14, s14, s39
	v_writelane_b32 v255, s43, 0
	s_bcnt1_i32_b64 s41, s[46:47]
	v_writelane_b32 v255, s48, 1
	s_add_i32 s14, s14, s40
	s_bcnt1_i32_b64 s42, s[42:43]
	v_cmp_gt_u32_e64 s[46:47], v49, v17
	v_writelane_b32 v255, s49, 2
	s_add_i32 s14, s14, s41
	s_bcnt1_i32_b64 s15, s[48:49]
	v_writelane_b32 v255, s46, 3
	s_add_i32 s14, s14, s42
	s_bcnt1_i32_b64 s16, s[46:47]
	v_writelane_b32 v255, s47, 4
	v_cmp_gt_u32_e64 s[46:47], v14, v17
	s_add_i32 s14, s14, s15
	s_bcnt1_i32_b64 s17, s[46:47]
	v_cmp_gt_u32_e64 s[20:21], v18, v17
	s_add_i32 s14, s14, s16
	s_bcnt1_i32_b64 s18, s[20:21]
	v_cmp_gt_u32_e64 s[22:23], v9, v17
	s_add_i32 s14, s14, s17
	v_cmp_gt_u32_e64 s[24:25], v6, v17
	s_bcnt1_i32_b64 s19, s[22:23]
	s_add_i32 s14, s14, s18
	s_bcnt1_i32_b64 s43, s[24:25]
	v_cmp_gt_u32_e64 s[30:31], v7, v17
	s_add_i32 s14, s14, s19
	v_cmp_gt_u32_e64 s[28:29], v4, v17
	s_bcnt1_i32_b64 s96, s[30:31]
	s_add_i32 s14, s14, s43
	s_bcnt1_i32_b64 s97, s[28:29]
	v_cmp_gt_u32_e64 s[26:27], v5, v17
	s_add_i32 s14, s14, s96
	v_cmp_gt_u32_e64 s[34:35], v0, v17
	s_bcnt1_i32_b64 vcc_lo, s[26:27]
	s_add_i32 s14, s14, s97
	s_bcnt1_i32_b64 s40, s[34:35]
	v_cmp_gt_u32_e64 s[36:37], v15, v17
	v_cmp_gt_u32_e64 s[42:43], v13, v17
	s_add_i32 s14, s14, vcc_lo
	v_cmp_gt_u32_e64 s[38:39], v12, v17
	s_bcnt1_i32_b64 s15, s[36:37]
	v_writelane_b32 v255, s42, 5
	s_add_i32 s14, s14, s40
	s_bcnt1_i32_b64 s16, s[38:39]
	v_cmp_gt_u32_e64 s[18:19], v10, v17
	v_writelane_b32 v255, s43, 6
	s_add_i32 s14, s14, s15
	s_bcnt1_i32_b64 s17, s[42:43]
	v_writelane_b32 v255, s18, 7
	s_add_i32 s14, s14, s16
	v_cmp_gt_u32_e64 s[40:41], v11, v17
	v_writelane_b32 v255, s19, 8
	s_bcnt1_i32_b64 s18, s[18:19]
	s_add_i32 s14, s14, s17
	v_writelane_b32 v255, s40, 9
	s_bcnt1_i32_b64 s15, s[40:41]
	s_add_i32 s14, s14, s18
	v_cmp_gt_u32_e64 s[42:43], v8, v17
	v_writelane_b32 v255, s41, 10
	s_add_i32 s14, s14, s15
	s_bcnt1_i32_b64 s15, s[42:43]
	v_cmp_gt_u32_e64 s[40:41], v16, v17
	v_cmp_eq_u32_e64 s[96:97], v35, v17
	s_add_i32 s14, s14, s15
	s_bcnt1_i32_b64 s15, s[40:41]
	v_and_b32_e32 v20, s96, v178
	s_add_i32 s14, s14, s15
	v_and_b32_e32 v19, s97, v179
	v_bcnt_u32_b32 v20, v20, 0
	s_sub_i32 s16, 0x100, s14
	v_bcnt_u32_b32 v19, v19, v20
	v_cmp_gt_i32_e32 vcc, s16, v19
	s_and_b64 s[14:15], s[96:97], vcc
	v_cndmask_b32_e64 v19, 0, 1, s[14:15]
	v_cmp_ne_u32_e32 vcc, 0, v19
	s_and_saveexec_b64 s[14:15], s[74:75]
	s_cbranch_execz .LBB0_519
	s_or_b64 s[12:13], vcc, s[12:13]
	v_mov_b64_e32 v[20:21], s[12:13]
	global_store_dwordx2 v[2:3], v[20:21], off

.LBB0_729:
	v_lshlrev_b32_e64 v20, v19, 1
	v_or_b32_e32 v20, v20, v17
	v_mov_b32_e32 v248, 0
	v_cmp_ge_u32_e64 s[4:5], v35, v20
	v_cmp_ge_u32_e64 s[6:7], v34, v20
	v_cmp_ge_u32_e64 s[8:9], v33, v20
	v_addc_co_u32_e64 v248, s[18:19], 0, v248, s[4:5]
	v_cmp_ge_u32_e64 s[4:5], v32, v20
	v_addc_co_u32_e64 v248, s[18:19], 0, v248, s[6:7]
	v_cmp_ge_u32_e64 s[6:7], v30, v20
	v_addc_co_u32_e64 v248, s[18:19], 0, v248, s[8:9]
	v_cmp_ge_u32_e64 s[8:9], v36, v20
	v_addc_co_u32_e64 v248, s[18:19], 0, v248, s[4:5]
	v_cmp_ge_u32_e64 s[4:5], v47, v20
	v_addc_co_u32_e64 v248, s[18:19], 0, v248, s[6:7]
	v_cmp_ge_u32_e64 s[6:7], v46, v20
	v_addc_co_u32_e64 v248, s[18:19], 0, v248, s[8:9]
	v_cmp_ge_u32_e64 s[8:9], v45, v20
	v_addc_co_u32_e64 v248, s[18:19], 0, v248, s[4:5]
	v_cmp_ge_u32_e64 s[4:5], v44, v20
	v_addc_co_u32_e64 v248, s[18:19], 0, v248, s[6:7]
	v_cmp_ge_u32_e64 s[6:7], v43, v20
	v_addc_co_u32_e64 v248, s[18:19], 0, v248, s[8:9]
	v_cmp_ge_u32_e64 s[8:9], v41, v20
	v_addc_co_u32_e64 v248, s[18:19], 0, v248, s[4:5]
	v_cmp_ge_u32_e64 s[4:5], v40, v20
	v_addc_co_u32_e64 v248, s[18:19], 0, v248, s[6:7]
	v_cmp_ge_u32_e64 s[6:7], v42, v20
	v_addc_co_u32_e64 v248, s[18:19], 0, v248, s[8:9]
	v_cmp_ge_u32_e64 s[8:9], v39, v20
	v_addc_co_u32_e64 v248, s[18:19], 0, v248, s[4:5]
	v_cmp_ge_u32_e64 s[4:5], v38, v20
	v_addc_co_u32_e64 v248, s[18:19], 0, v248, s[6:7]
	v_cmp_ge_u32_e64 s[6:7], v37, v20
	v_addc_co_u32_e64 v248, s[18:19], 0, v248, s[8:9]
	v_cmp_ge_u32_e64 s[8:9], v14, v20
	v_addc_co_u32_e64 v248, s[18:19], 0, v248, s[4:5]
	v_cmp_ge_u32_e64 s[4:5], v18, v20
	v_addc_co_u32_e64 v248, s[18:19], 0, v248, s[6:7]
	v_cmp_ge_u32_e64 s[6:7], v9, v20
	v_addc_co_u32_e64 v248, s[18:19], 0, v248, s[8:9]
	v_cmp_ge_u32_e64 s[8:9], v6, v20
	v_addc_co_u32_e64 v248, s[18:19], 0, v248, s[4:5]
	v_cmp_ge_u32_e64 s[4:5], v7, v20
	v_addc_co_u32_e64 v248, s[18:19], 0, v248, s[6:7]
	v_cmp_ge_u32_e64 s[6:7], v4, v20
	v_addc_co_u32_e64 v248, s[18:19], 0, v248, s[8:9]
	v_cmp_ge_u32_e64 s[8:9], v5, v20
	v_addc_co_u32_e64 v248, s[18:19], 0, v248, s[4:5]
	v_cmp_ge_u32_e64 s[4:5], v0, v20
	v_addc_co_u32_e64 v248, s[18:19], 0, v248, s[6:7]
	v_cmp_ge_u32_e64 s[6:7], v15, v20
	v_addc_co_u32_e64 v248, s[18:19], 0, v248, s[8:9]
	v_cmp_ge_u32_e64 s[8:9], v12, v20
	v_addc_co_u32_e64 v248, s[18:19], 0, v248, s[4:5]
	v_cmp_ge_u32_e64 s[4:5], v13, v20
	v_addc_co_u32_e64 v248, s[18:19], 0, v248, s[6:7]
	v_cmp_ge_u32_e64 s[6:7], v10, v20
	v_addc_co_u32_e64 v248, s[18:19], 0, v248, s[8:9]
	v_cmp_ge_u32_e64 s[8:9], v11, v20
	v_addc_co_u32_e64 v248, s[18:19], 0, v248, s[4:5]
	v_cmp_ge_u32_e64 s[4:5], v8, v20
	v_addc_co_u32_e64 v248, s[18:19], 0, v248, s[6:7]
	v_cmp_ge_u32_e64 s[6:7], v16, v20
	v_addc_co_u32_e64 v248, s[18:19], 0, v248, s[8:9]
	v_addc_co_u32_e64 v248, s[18:19], 0, v248, s[4:5]
	v_addc_co_u32_e64 v248, s[18:19], 0, v248, s[6:7]
	s_nop 1
	v_add_u32_dpp v248, v248, v248 quad_perm:[1,0,3,2] row_mask:0xf bank_mask:0xf
	s_nop 1
	v_add_u32_dpp v248, v248, v248 quad_perm:[2,3,0,1] row_mask:0xf bank_mask:0xf
	s_nop 1
	v_add_u32_dpp v248, v248, v248 row_half_mirror row_mask:0xf bank_mask:0xf
	s_nop 1
	v_add_u32_dpp v248, v248, v248 row_mirror row_mask:0xf bank_mask:0xf
	s_nop 1
	v_add_u32_dpp v248, v248, v248 row_bcast:15 row_mask:0xa bank_mask:0xf
	s_nop 1
	v_add_u32_dpp v248, v248, v248 row_bcast:31 row_mask:0xc bank_mask:0xf
	s_nop 1
	v_readlane_b32 s2, v248, 63
	s_cmpk_gt_u32 s2, 0xff
	s_cselect_b64 vcc, -1, 0
	s_cmpk_lg_i32 s2, 0x100
	s_cselect_b64 s[0:1], -1, 0
	s_cmpk_eq_i32 s2, 0x100
	v_cndmask_b32_e32 v17, v17, v20, vcc
	s_cselect_b64 s[2:3], -1, 0
	v_subrev_co_u32_e32 v19, vcc, 1, v19
	s_or_b64 s[2:3], s[2:3], vcc
	s_andn2_b64 vcc, exec, s[2:3]
	s_cbranch_vccnz .LBB0_729
	s_andn2_b64 vcc, exec, s[0:1]
	s_mov_b64 s[0:1], -1
	s_cbranch_vccnz .LBB0_796
	v_cmp_gt_u32_e64 s[62:63], v35, v17
	v_cmp_gt_u32_e64 s[60:61], v34, v17
	s_bcnt1_i32_b64 s0, s[62:63]
	s_bcnt1_i32_b64 s1, s[60:61]
	v_cmp_gt_u32_e64 s[58:59], v33, v17
	s_bcnt1_i32_b64 s64, s[58:59]
	v_cmp_gt_u32_e64 s[56:57], v32, v17
	s_add_i32 s0, s0, s1
	s_bcnt1_i32_b64 s65, s[56:57]
	v_cmp_gt_u32_e64 s[54:55], v30, v17
	s_add_i32 s0, s0, s64
	v_cmp_gt_u32_e64 s[52:53], v36, v17
	s_bcnt1_i32_b64 s66, s[54:55]
	s_add_i32 s64, s0, s65
	s_bcnt1_i32_b64 s67, s[52:53]
	v_cmp_gt_u32_e64 s[50:51], v47, v17
	s_add_i32 s64, s64, s66
	s_bcnt1_i32_b64 s68, s[50:51]
	v_cmp_gt_u32_e64 s[48:49], v46, v17
	s_add_i32 s64, s64, s67
	v_cmp_gt_u32_e64 s[46:47], v45, v17
	s_bcnt1_i32_b64 s69, s[48:49]
	s_add_i32 s64, s64, s68
	s_bcnt1_i32_b64 s70, s[46:47]
	v_cmp_gt_u32_e64 s[44:45], v44, v17
	s_add_i32 s64, s64, s69
	v_cmp_gt_u32_e64 s[42:43], v43, v17
	s_bcnt1_i32_b64 s71, s[44:45]
	s_add_i32 s64, s64, s70
	s_bcnt1_i32_b64 s72, s[42:43]
	v_cmp_gt_u32_e64 s[40:41], v41, v17
	s_add_i32 s64, s64, s71
	v_cmp_gt_u32_e64 s[38:39], v40, v17
	s_bcnt1_i32_b64 s73, s[40:41]
	s_add_i32 s64, s64, s72
	s_bcnt1_i32_b64 s74, s[38:39]
	v_cmp_gt_u32_e64 s[36:37], v42, v17
	s_add_i32 s64, s64, s73
	v_cmp_gt_u32_e64 s[34:35], v39, v17
	s_bcnt1_i32_b64 s75, s[36:37]
	s_add_i32 s64, s64, s74
	s_bcnt1_i32_b64 s76, s[34:35]
	v_cmp_gt_u32_e64 s[30:31], v38, v17
	s_add_i32 s64, s64, s75
	v_cmp_gt_u32_e64 s[28:29], v37, v17
	s_bcnt1_i32_b64 s77, s[30:31]
	s_add_i32 s64, s64, s76
	s_bcnt1_i32_b64 s78, s[28:29]
	v_cmp_gt_u32_e64 s[26:27], v14, v17
	s_add_i32 s64, s64, s77
	s_bcnt1_i32_b64 s79, s[26:27]
	v_cmp_gt_u32_e64 s[24:25], v18, v17
	s_add_i32 s64, s64, s78
	s_bcnt1_i32_b64 s80, s[24:25]
	v_cmp_gt_u32_e64 s[22:23], v9, v17
	s_add_i32 s64, s64, s79
	v_cmp_gt_u32_e64 s[20:21], v6, v17
	s_bcnt1_i32_b64 s81, s[22:23]
	s_add_i32 s64, s64, s80
	s_bcnt1_i32_b64 s82, s[20:21]
	v_cmp_gt_u32_e64 s[18:19], v7, v17
	s_add_i32 s64, s64, s81
	v_cmp_gt_u32_e64 s[16:17], v4, v17
	s_bcnt1_i32_b64 s83, s[18:19]
	s_add_i32 s64, s64, s82
	s_bcnt1_i32_b64 s84, s[16:17]
	v_cmp_gt_u32_e64 s[14:15], v5, v17
	s_add_i32 s64, s64, s83
	v_cmp_gt_u32_e64 s[10:11], v0, v17
	s_bcnt1_i32_b64 s85, s[14:15]
	s_add_i32 s64, s64, s84
	s_bcnt1_i32_b64 s86, s[10:11]
	v_cmp_gt_u32_e64 s[4:5], v15, v17
	s_add_i32 s64, s64, s85
	v_cmp_gt_u32_e64 s[8:9], v12, v17
	s_bcnt1_i32_b64 s87, s[4:5]
	s_add_i32 s64, s64, s86
	s_bcnt1_i32_b64 s88, s[8:9]
	v_cmp_gt_u32_e64 s[6:7], v13, v17
	s_add_i32 s64, s64, s87
	v_cmp_gt_u32_e64 s[12:13], v10, v17
	s_bcnt1_i32_b64 s89, s[6:7]
	s_add_i32 s64, s64, s88
	s_bcnt1_i32_b64 s90, s[12:13]
	v_cmp_gt_u32_e64 s[0:1], v11, v17
	s_add_i32 s64, s64, s89
	v_cmp_gt_u32_e64 s[2:3], v8, v17
	s_bcnt1_i32_b64 s65, s[0:1]
	s_add_i32 s64, s64, s90
	s_bcnt1_i32_b64 s66, s[2:3]
	v_cmp_gt_u32_e32 vcc, v16, v17
	s_add_i32 s64, s64, s65
	s_bcnt1_i32_b64 s67, vcc
	s_add_i32 s64, s64, s66
	s_add_i32 s64, s64, s67
	s_sub_i32 s70, 0x100, s64
	v_cmp_eq_u32_e64 s[64:65], v35, v17
	v_readlane_b32 s74, v254, 56
	v_readlane_b32 s75, v254, 57
	v_and_b32_e32 v20, s64, v178
	v_and_b32_e32 v19, s65, v179
	v_bcnt_u32_b32 v20, v20, 0
	v_bcnt_u32_b32 v19, v19, v20
	v_cmp_gt_i32_e64 s[66:67], s70, v19
	s_and_b64 s[66:67], s[64:65], s[66:67]
	s_nop 0
	v_cndmask_b32_e64 v19, 0, 1, s[66:67]
	v_cmp_ne_u32_e64 s[66:67], 0, v19
	s_and_saveexec_b64 s[68:69], s[74:75]
	s_cbranch_execz .LBB0_733
	s_or_b64 s[62:63], s[66:67], s[62:63]
	v_mov_b64_e32 v[20:21], s[62:63]
	global_store_dwordx2 v[2:3], v[20:21], off

.LBB0_833:
	v_lshlrev_b32_e64 v16, v15, 1
	v_or_b32_e32 v16, v16, v13
	v_mov_b32_e32 v248, 0
	v_cmp_ge_u32_e64 s[4:5], v35, v16
	v_cmp_ge_u32_e64 s[6:7], v34, v16
	v_cmp_ge_u32_e64 s[8:9], v33, v16
	v_addc_co_u32_e64 v248, s[18:19], 0, v248, s[4:5]
	v_cmp_ge_u32_e64 s[4:5], v32, v16
	v_addc_co_u32_e64 v248, s[18:19], 0, v248, s[6:7]
	v_cmp_ge_u32_e64 s[6:7], v30, v16
	v_addc_co_u32_e64 v248, s[18:19], 0, v248, s[8:9]
	v_cmp_ge_u32_e64 s[8:9], v10, v16
	v_addc_co_u32_e64 v248, s[18:19], 0, v248, s[4:5]
	v_cmp_ge_u32_e64 s[4:5], v14, v16
	v_addc_co_u32_e64 v248, s[18:19], 0, v248, s[6:7]
	v_cmp_ge_u32_e64 s[6:7], v11, v16
	v_addc_co_u32_e64 v248, s[18:19], 0, v248, s[8:9]
	v_cmp_ge_u32_e64 s[8:9], v8, v16
	v_addc_co_u32_e64 v248, s[18:19], 0, v248, s[4:5]
	v_cmp_ge_u32_e64 s[4:5], v7, v16
	v_addc_co_u32_e64 v248, s[18:19], 0, v248, s[6:7]
	v_cmp_ge_u32_e64 s[6:7], v4, v16
	v_addc_co_u32_e64 v248, s[18:19], 0, v248, s[8:9]
	v_cmp_ge_u32_e64 s[8:9], v9, v16
	v_addc_co_u32_e64 v248, s[18:19], 0, v248, s[4:5]
	v_cmp_ge_u32_e64 s[4:5], v6, v16
	v_addc_co_u32_e64 v248, s[18:19], 0, v248, s[6:7]
	v_cmp_ge_u32_e64 s[6:7], v5, v16
	v_addc_co_u32_e64 v248, s[18:19], 0, v248, s[8:9]
	v_cmp_ge_u32_e64 s[8:9], v0, v16
	v_addc_co_u32_e64 v248, s[18:19], 0, v248, s[4:5]
	v_cmp_ge_u32_e64 s[4:5], v12, v16
	v_addc_co_u32_e64 v248, s[18:19], 0, v248, s[6:7]
	v_addc_co_u32_e64 v248, s[18:19], 0, v248, s[8:9]
	v_addc_co_u32_e64 v248, s[18:19], 0, v248, s[4:5]
	s_nop 1
	v_add_u32_dpp v248, v248, v248 quad_perm:[1,0,3,2] row_mask:0xf bank_mask:0xf
	s_nop 1
	v_add_u32_dpp v248, v248, v248 quad_perm:[2,3,0,1] row_mask:0xf bank_mask:0xf
	s_nop 1
	v_add_u32_dpp v248, v248, v248 row_half_mirror row_mask:0xf bank_mask:0xf
	s_nop 1
	v_add_u32_dpp v248, v248, v248 row_mirror row_mask:0xf bank_mask:0xf
	s_nop 1
	v_add_u32_dpp v248, v248, v248 row_bcast:15 row_mask:0xa bank_mask:0xf
	s_nop 1
	v_add_u32_dpp v248, v248, v248 row_bcast:31 row_mask:0xc bank_mask:0xf
	s_nop 1
	v_readlane_b32 s2, v248, 63
	s_cmpk_gt_u32 s2, 0xff
	s_cselect_b64 vcc, -1, 0
	s_cmpk_lg_i32 s2, 0x100
	s_cselect_b64 s[0:1], -1, 0
	s_cmpk_eq_i32 s2, 0x100
	v_cndmask_b32_e32 v13, v13, v16, vcc
	s_cselect_b64 s[2:3], -1, 0
	v_subrev_co_u32_e32 v15, vcc, 1, v15
	s_or_b64 s[2:3], s[2:3], vcc
	s_andn2_b64 vcc, exec, s[2:3]
	s_cbranch_vccnz .LBB0_833
	s_andn2_b64 vcc, exec, s[0:1]
	s_mov_b64 s[0:1], -1
	s_cbranch_vccnz .LBB0_868
	v_cmp_gt_u32_e64 s[28:29], v35, v13
	v_cmp_gt_u32_e64 s[26:27], v34, v13
	s_bcnt1_i32_b64 s30, s[28:29]
	v_cmp_gt_u32_e64 s[24:25], v33, v13
	s_bcnt1_i32_b64 s31, s[26:27]
	s_bcnt1_i32_b64 s34, s[24:25]
	v_cmp_gt_u32_e64 s[22:23], v32, v13
	s_add_i32 s30, s30, s31
	v_cmp_gt_u32_e64 s[20:21], v30, v13
	s_bcnt1_i32_b64 s35, s[22:23]
	s_add_i32 s30, s30, s34
	s_bcnt1_i32_b64 s36, s[20:21]
	v_cmp_gt_u32_e64 s[18:19], v10, v13
	s_add_i32 s30, s30, s35
	s_bcnt1_i32_b64 s37, s[18:19]
	v_cmp_gt_u32_e64 s[16:17], v14, v13
	s_add_i32 s30, s30, s36
	s_bcnt1_i32_b64 s38, s[16:17]
	v_cmp_gt_u32_e64 s[14:15], v11, v13
	s_add_i32 s30, s30, s37
	v_cmp_gt_u32_e64 s[12:13], v8, v13
	s_bcnt1_i32_b64 s39, s[14:15]
	s_add_i32 s30, s30, s38
	s_bcnt1_i32_b64 s40, s[12:13]
	v_cmp_gt_u32_e64 s[10:11], v7, v13
	s_add_i32 s30, s30, s39
	v_cmp_gt_u32_e64 s[8:9], v4, v13
	s_bcnt1_i32_b64 s41, s[10:11]
	s_add_i32 s30, s30, s40
	s_bcnt1_i32_b64 s42, s[8:9]
	v_cmp_gt_u32_e64 s[6:7], v9, v13
	s_add_i32 s30, s30, s41
	v_cmp_gt_u32_e64 s[4:5], v6, v13
	s_bcnt1_i32_b64 s43, s[6:7]
	s_add_i32 s30, s30, s42
	s_bcnt1_i32_b64 s44, s[4:5]
	v_cmp_gt_u32_e64 s[2:3], v5, v13
	s_add_i32 s30, s30, s43
	v_cmp_gt_u32_e64 s[0:1], v0, v13
	s_bcnt1_i32_b64 s45, s[2:3]
	s_add_i32 s30, s30, s44
	s_bcnt1_i32_b64 s46, s[0:1]
	v_cmp_gt_u32_e32 vcc, v12, v13
	s_add_i32 s30, s30, s45
	s_bcnt1_i32_b64 s47, vcc
	s_add_i32 s30, s30, s46
	s_add_i32 s30, s30, s47
	s_sub_i32 s38, 0x100, s30
	v_cmp_eq_u32_e64 s[30:31], v35, v13
	s_nop 1
	v_and_b32_e32 v16, s30, v178
	v_and_b32_e32 v15, s31, v179
	v_bcnt_u32_b32 v16, v16, 0
	v_bcnt_u32_b32 v15, v15, v16
	v_cmp_gt_i32_e64 s[34:35], s38, v15
	s_and_b64 s[34:35], s[30:31], s[34:35]
	s_nop 0
	v_cndmask_b32_e64 v15, 0, 1, s[34:35]
	v_cmp_ne_u32_e64 s[34:35], 0, v15
	s_and_saveexec_b64 s[36:37], s[74:75]
	s_cbranch_execz .LBB0_837
	s_or_b64 s[28:29], s[34:35], s[28:29]
	v_mov_b64_e32 v[16:17], s[28:29]
	global_store_dwordx2 v[2:3], v[16:17], off

.LBB0_1371:
	s_or_b64 exec, exec, s[22:23]
	v_cmp_le_i32_e32 vcc, s34, v226
	s_and_saveexec_b64 s[22:23], vcc
	s_cbranch_execz .LBB0_1373
	ds_read_b64 v[6:7], v228 offset:8192
	ds_read_b64 v[8:9], v229 offset:8192
	ds_read_b64 v[10:11], v230 offset:20480
	ds_read_b64 v[12:13], v231 offset:20480
	ds_read_b64 v[244:245], v230 offset:12288
	ds_read_b64 v[246:247], v231 offset:12288
	v_exp_f32_e32 v32, v32
	v_exp_f32_e32 v33, v33
	v_exp_f32_e32 v34, v34
	v_exp_f32_e32 v35, v35
	v_exp_f32_e32 v36, v36
	v_exp_f32_e32 v37, v37
	v_exp_f32_e32 v38, v38
	v_exp_f32_e32 v39, v39
	v_cvt_pk_bf16_f32 v2, v32, v33
	v_cvt_pk_bf16_f32 v3, v34, v35
	v_cvt_pk_bf16_f32 v4, v36, v37
	v_cvt_pk_bf16_f32 v5, v38, v39
	v_add_f32_e32 v0, 0, v32
	v_add_f32_e32 v0, v33, v0
	v_add_f32_e32 v0, v34, v0
	v_add_f32_e32 v0, v35, v0
	v_add_f32_e32 v0, v36, v0
	v_add_f32_e32 v0, v37, v0
	v_add_f32_e32 v0, v38, v0
	v_add_f32_e32 v0, v39, v0
	ds_read_b64 v[32:33], v230 offset:16384
	ds_read_b64 v[34:35], v231 offset:16384
	ds_read_b64 v[36:37], v232 offset:8192
	ds_read_b64 v[38:39], v233 offset:8192
	s_waitcnt lgkmcnt(8)
	v_mfma_f32_32x32x16_bf16 v[112:127], v[6:9], v[2:5], v[112:127]
	ds_read_b64 v[6:7], v234 offset:20480
	ds_read_b64 v[8:9], v235 offset:20480
	v_exp_f32_e32 v40, v40
	v_exp_f32_e32 v41, v41
	s_waitcnt lgkmcnt(8)
	v_mfma_f32_32x32x16_bf16 v[64:79], v[10:13], v[2:5], v[64:79]
	ds_read_b64 v[10:11], v234 offset:12288
	ds_read_b64 v[12:13], v235 offset:12288
	v_exp_f32_e32 v42, v42
	v_exp_f32_e32 v43, v43
	v_add_f32_e32 v0, v40, v0
	v_add_f32_e32 v0, v41, v0
	s_waitcnt lgkmcnt(8)
	v_mfma_f32_32x32x16_bf16 v[96:111], v[244:247], v[2:5], v[96:111]
	ds_read_b64 v[244:245], v234 offset:16384
	ds_read_b64 v[246:247], v235 offset:16384
	v_exp_f32_e32 v44, v44
	v_exp_f32_e32 v45, v45
	v_add_f32_e32 v0, v42, v0
	v_add_f32_e32 v0, v43, v0
	s_waitcnt lgkmcnt(8)
	v_mfma_f32_32x32x16_bf16 v[80:95], v[32:35], v[2:5], v[80:95]
	ds_read_b64 v[32:33], v236 offset:8192
	ds_read_b64 v[34:35], v237 offset:8192
	v_exp_f32_e32 v46, v46
	v_exp_f32_e32 v47, v47
	v_add_f32_e32 v0, v44, v0
	v_add_f32_e32 v0, v45, v0
	v_add_f32_e32 v0, v46, v0
	v_add_f32_e32 v0, v47, v0
	v_cvt_pk_bf16_f32 v2, v40, v41
	v_cvt_pk_bf16_f32 v3, v42, v43
	v_cvt_pk_bf16_f32 v4, v44, v45
	v_cvt_pk_bf16_f32 v5, v46, v47
	s_nop 1
	ds_read_b64 v[40:41], v238 offset:20480
	ds_read_b64 v[42:43], v239 offset:20480
	s_waitcnt lgkmcnt(10)
	v_mfma_f32_32x32x16_bf16 v[112:127], v[36:39], v[2:5], v[112:127]
	ds_read_b64 v[44:45], v238 offset:12288
	ds_read_b64 v[46:47], v239 offset:12288
	v_exp_f32_e32 v48, v48
	v_exp_f32_e32 v49, v49
	s_waitcnt lgkmcnt(10)
	v_mfma_f32_32x32x16_bf16 v[64:79], v[6:9], v[2:5], v[64:79]
	ds_read_b64 v[36:37], v238 offset:16384
	ds_read_b64 v[38:39], v239 offset:16384
	v_exp_f32_e32 v50, v50
	v_exp_f32_e32 v51, v51
	v_add_f32_e32 v0, v48, v0
	v_add_f32_e32 v0, v49, v0
	s_waitcnt lgkmcnt(10)
	v_mfma_f32_32x32x16_bf16 v[96:111], v[10:13], v[2:5], v[96:111]
	ds_read_b64 v[6:7], v240 offset:8192
	ds_read_b64 v[8:9], v241 offset:8192
	v_exp_f32_e32 v52, v52
	v_exp_f32_e32 v53, v53
	v_add_f32_e32 v0, v50, v0
	v_add_f32_e32 v0, v51, v0
	s_waitcnt lgkmcnt(10)
	v_mfma_f32_32x32x16_bf16 v[80:95], v[244:247], v[2:5], v[80:95]
	ds_read_b64 v[10:11], v242 offset:12288
	ds_read_b64 v[12:13], v243 offset:12288
	v_exp_f32_e32 v54, v54
	v_exp_f32_e32 v55, v55
	v_add_f32_e32 v0, v52, v0
	v_add_f32_e32 v0, v53, v0
	v_add_f32_e32 v0, v54, v0
	v_add_f32_e32 v0, v55, v0
	v_cvt_pk_bf16_f32 v2, v48, v49
	v_cvt_pk_bf16_f32 v3, v50, v51
	v_cvt_pk_bf16_f32 v4, v52, v53
	v_cvt_pk_bf16_f32 v5, v54, v55
	s_nop 1
	ds_read_b64 v[244:245], v242 offset:16384
	ds_read_b64 v[246:247], v243 offset:16384
	s_waitcnt lgkmcnt(12)
	v_mfma_f32_32x32x16_bf16 v[112:127], v[32:35], v[2:5], v[112:127]
	ds_read_b64 v[48:49], v242 offset:20480
	ds_read_b64 v[50:51], v243 offset:20480
	v_exp_f32_e32 v56, v56
	v_exp_f32_e32 v57, v57
	s_waitcnt lgkmcnt(12)
	v_mfma_f32_32x32x16_bf16 v[64:79], v[40:43], v[2:5], v[64:79]
	v_exp_f32_e32 v58, v58
	v_exp_f32_e32 v59, v59
	v_add_f32_e32 v0, v56, v0
	v_add_f32_e32 v0, v57, v0
	s_waitcnt lgkmcnt(10)
	v_mfma_f32_32x32x16_bf16 v[96:111], v[44:47], v[2:5], v[96:111]
	v_exp_f32_e32 v60, v60
	v_exp_f32_e32 v61, v61
	v_add_f32_e32 v0, v58, v0
	v_add_f32_e32 v0, v59, v0
	s_waitcnt lgkmcnt(8)
	v_mfma_f32_32x32x16_bf16 v[80:95], v[36:39], v[2:5], v[80:95]
	v_exp_f32_e32 v62, v62
	v_exp_f32_e32 v63, v63
	v_add_f32_e32 v0, v60, v0
	v_add_f32_e32 v0, v61, v0
	v_add_f32_e32 v0, v62, v0
	v_add_f32_e32 v0, v63, v0
	v_cvt_pk_bf16_f32 v2, v56, v57
	v_cvt_pk_bf16_f32 v3, v58, v59
	v_cvt_pk_bf16_f32 v4, v60, v61
	v_cvt_pk_bf16_f32 v5, v62, v63
	s_nop 1
	s_waitcnt lgkmcnt(6)
	v_mfma_f32_32x32x16_bf16 v[112:127], v[6:9], v[2:5], v[112:127]
	s_waitcnt lgkmcnt(4)
	v_mfma_f32_32x32x16_bf16 v[96:111], v[10:13], v[2:5], v[96:111]
	s_waitcnt lgkmcnt(2)
	v_mfma_f32_32x32x16_bf16 v[80:95], v[244:247], v[2:5], v[80:95]
	s_waitcnt lgkmcnt(0)
	v_mfma_f32_32x32x16_bf16 v[64:79], v[48:51], v[2:5], v[64:79]
	v_add_f32_e32 v227, v227, v0

.LBB0_1385:
	ds_read_b64 v[6:7], v228 offset:32768
	ds_read_b64 v[8:9], v229 offset:32768
	ds_read_b64 v[10:11], v230 offset:45056
	ds_read_b64 v[12:13], v231 offset:45056
	ds_read_b64 v[244:245], v230 offset:36864
	ds_read_b64 v[246:247], v231 offset:36864
	v_exp_f32_e32 v128, v128
	v_exp_f32_e32 v129, v129
	v_exp_f32_e32 v130, v130
	v_exp_f32_e32 v131, v131
	v_exp_f32_e32 v132, v132
	v_exp_f32_e32 v133, v133
	v_exp_f32_e32 v134, v134
	v_exp_f32_e32 v135, v135
	v_cvt_pk_bf16_f32 v2, v128, v129
	v_cvt_pk_bf16_f32 v3, v130, v131
	v_cvt_pk_bf16_f32 v4, v132, v133
	v_cvt_pk_bf16_f32 v5, v134, v135
	v_add_f32_e32 v0, 0, v128
	v_add_f32_e32 v0, v129, v0
	v_add_f32_e32 v0, v130, v0
	v_add_f32_e32 v0, v131, v0
	v_add_f32_e32 v0, v132, v0
	v_add_f32_e32 v0, v133, v0
	v_add_f32_e32 v0, v134, v0
	v_add_f32_e32 v0, v135, v0
	ds_read_b64 v[128:129], v230 offset:40960
	ds_read_b64 v[130:131], v231 offset:40960
	ds_read_b64 v[132:133], v232 offset:32768
	ds_read_b64 v[134:135], v233 offset:32768
	s_waitcnt lgkmcnt(8)
	v_mfma_f32_32x32x16_bf16 v[112:127], v[6:9], v[2:5], v[112:127]
	ds_read_b64 v[6:7], v234 offset:45056
	ds_read_b64 v[8:9], v235 offset:45056
	v_exp_f32_e32 v136, v136
	v_exp_f32_e32 v137, v137
	s_waitcnt lgkmcnt(8)
	v_mfma_f32_32x32x16_bf16 v[64:79], v[10:13], v[2:5], v[64:79]
	ds_read_b64 v[10:11], v234 offset:36864
	ds_read_b64 v[12:13], v235 offset:36864
	v_exp_f32_e32 v138, v138
	v_exp_f32_e32 v139, v139
	v_add_f32_e32 v0, v136, v0
	v_add_f32_e32 v0, v137, v0
	s_waitcnt lgkmcnt(8)
	v_mfma_f32_32x32x16_bf16 v[96:111], v[244:247], v[2:5], v[96:111]
	ds_read_b64 v[244:245], v234 offset:40960
	ds_read_b64 v[246:247], v235 offset:40960
	v_exp_f32_e32 v140, v140
	v_exp_f32_e32 v141, v141
	v_add_f32_e32 v0, v138, v0
	v_add_f32_e32 v0, v139, v0
	s_waitcnt lgkmcnt(8)
	v_mfma_f32_32x32x16_bf16 v[80:95], v[128:131], v[2:5], v[80:95]
	ds_read_b64 v[128:129], v236 offset:32768
	ds_read_b64 v[130:131], v237 offset:32768
	v_exp_f32_e32 v142, v142
	v_exp_f32_e32 v143, v143
	v_add_f32_e32 v0, v140, v0
	v_add_f32_e32 v0, v141, v0
	v_add_f32_e32 v0, v142, v0
	v_add_f32_e32 v0, v143, v0
	v_cvt_pk_bf16_f32 v2, v136, v137
	v_cvt_pk_bf16_f32 v3, v138, v139
	v_cvt_pk_bf16_f32 v4, v140, v141
	v_cvt_pk_bf16_f32 v5, v142, v143
	s_nop 1
	ds_read_b64 v[136:137], v238 offset:45056
	ds_read_b64 v[138:139], v239 offset:45056
	s_waitcnt lgkmcnt(10)
	v_mfma_f32_32x32x16_bf16 v[112:127], v[132:135], v[2:5], v[112:127]
	ds_read_b64 v[140:141], v238 offset:36864
	ds_read_b64 v[142:143], v239 offset:36864
	v_exp_f32_e32 v144, v144
	v_exp_f32_e32 v145, v145
	s_waitcnt lgkmcnt(10)
	v_mfma_f32_32x32x16_bf16 v[64:79], v[6:9], v[2:5], v[64:79]
	ds_read_b64 v[132:133], v238 offset:40960
	ds_read_b64 v[134:135], v239 offset:40960
	v_exp_f32_e32 v146, v146
	v_exp_f32_e32 v147, v147
	v_add_f32_e32 v0, v144, v0
	v_add_f32_e32 v0, v145, v0
	s_waitcnt lgkmcnt(10)
	v_mfma_f32_32x32x16_bf16 v[96:111], v[10:13], v[2:5], v[96:111]
	ds_read_b64 v[6:7], v240 offset:32768
	ds_read_b64 v[8:9], v241 offset:32768
	v_exp_f32_e32 v148, v148
	v_exp_f32_e32 v149, v149
	v_add_f32_e32 v0, v146, v0
	v_add_f32_e32 v0, v147, v0
	s_waitcnt lgkmcnt(10)
	v_mfma_f32_32x32x16_bf16 v[80:95], v[244:247], v[2:5], v[80:95]
	ds_read_b64 v[10:11], v242 offset:36864
	ds_read_b64 v[12:13], v243 offset:36864
	v_exp_f32_e32 v150, v150
	v_exp_f32_e32 v151, v151
	v_add_f32_e32 v0, v148, v0
	v_add_f32_e32 v0, v149, v0
	v_add_f32_e32 v0, v150, v0
	v_add_f32_e32 v0, v151, v0
	v_cvt_pk_bf16_f32 v2, v144, v145
	v_cvt_pk_bf16_f32 v3, v146, v147
	v_cvt_pk_bf16_f32 v4, v148, v149
	v_cvt_pk_bf16_f32 v5, v150, v151
	s_nop 1
	ds_read_b64 v[244:245], v242 offset:40960
	ds_read_b64 v[246:247], v243 offset:40960
	s_waitcnt lgkmcnt(12)
	v_mfma_f32_32x32x16_bf16 v[112:127], v[128:131], v[2:5], v[112:127]
	ds_read_b64 v[144:145], v242 offset:45056
	ds_read_b64 v[146:147], v243 offset:45056
	v_exp_f32_e32 v152, v152
	v_exp_f32_e32 v153, v153
	s_waitcnt lgkmcnt(12)
	v_mfma_f32_32x32x16_bf16 v[64:79], v[136:139], v[2:5], v[64:79]
	v_exp_f32_e32 v154, v154
	v_exp_f32_e32 v155, v155
	v_add_f32_e32 v0, v152, v0
	v_add_f32_e32 v0, v153, v0
	s_waitcnt lgkmcnt(10)
	v_mfma_f32_32x32x16_bf16 v[96:111], v[140:143], v[2:5], v[96:111]
	v_exp_f32_e32 v156, v156
	v_exp_f32_e32 v157, v157
	v_add_f32_e32 v0, v154, v0
	v_add_f32_e32 v0, v155, v0
	s_waitcnt lgkmcnt(8)
	v_mfma_f32_32x32x16_bf16 v[80:95], v[132:135], v[2:5], v[80:95]
	v_exp_f32_e32 v158, v158
	v_exp_f32_e32 v159, v159
	v_add_f32_e32 v0, v156, v0
	v_add_f32_e32 v0, v157, v0
	v_add_f32_e32 v0, v158, v0
	v_add_f32_e32 v0, v159, v0
	v_cvt_pk_bf16_f32 v2, v152, v153
	v_cvt_pk_bf16_f32 v3, v154, v155
	v_cvt_pk_bf16_f32 v4, v156, v157
	v_cvt_pk_bf16_f32 v5, v158, v159
	s_nop 1
	s_waitcnt lgkmcnt(6)
	v_mfma_f32_32x32x16_bf16 v[112:127], v[6:9], v[2:5], v[112:127]
	s_waitcnt lgkmcnt(4)
	v_mfma_f32_32x32x16_bf16 v[96:111], v[10:13], v[2:5], v[96:111]
	s_waitcnt lgkmcnt(2)
	v_mfma_f32_32x32x16_bf16 v[80:95], v[244:247], v[2:5], v[80:95]
	s_waitcnt lgkmcnt(0)
	v_mfma_f32_32x32x16_bf16 v[64:79], v[144:147], v[2:5], v[64:79]
	v_add_f32_e32 v227, v0, v227

.LBB0_1413:
	s_or_b64 exec, exec, s[22:23]
	v_cmp_le_i32_e32 vcc, s31, v225
	s_and_saveexec_b64 s[22:23], vcc
	s_cbranch_execz .LBB0_1415
	ds_read_b64 v[6:7], v226 offset:8192
	ds_read_b64 v[8:9], v227 offset:8192
	ds_read_b64 v[10:11], v228 offset:20480
	ds_read_b64 v[12:13], v229 offset:20480
	ds_read_b64 v[242:243], v228 offset:12288
	ds_read_b64 v[244:245], v229 offset:12288
	v_exp_f32_e32 v80, v80
	v_exp_f32_e32 v81, v81
	v_exp_f32_e32 v82, v82
	v_exp_f32_e32 v83, v83
	v_exp_f32_e32 v84, v84
	v_exp_f32_e32 v85, v85
	v_exp_f32_e32 v86, v86
	v_exp_f32_e32 v87, v87
	v_cvt_pk_bf16_f32 v2, v80, v81
	v_cvt_pk_bf16_f32 v3, v82, v83
	v_cvt_pk_bf16_f32 v4, v84, v85
	v_cvt_pk_bf16_f32 v5, v86, v87
	v_add_f32_e32 v0, 0, v80
	v_add_f32_e32 v0, v81, v0
	v_add_f32_e32 v0, v82, v0
	v_add_f32_e32 v0, v83, v0
	v_add_f32_e32 v0, v84, v0
	v_add_f32_e32 v0, v85, v0
	v_add_f32_e32 v0, v86, v0
	v_add_f32_e32 v0, v87, v0
	ds_read_b64 v[80:81], v228 offset:16384
	ds_read_b64 v[82:83], v229 offset:16384
	ds_read_b64 v[84:85], v230 offset:8192
	ds_read_b64 v[86:87], v231 offset:8192
	s_waitcnt lgkmcnt(8)
	v_mfma_f32_32x32x16_bf16 v[64:79], v[6:9], v[2:5], v[64:79]
	ds_read_b64 v[6:7], v232 offset:20480
	ds_read_b64 v[8:9], v233 offset:20480
	v_exp_f32_e32 v88, v88
	v_exp_f32_e32 v89, v89
	s_waitcnt lgkmcnt(8)
	v_mfma_f32_32x32x16_bf16 v[112:127], v[10:13], v[2:5], v[112:127]
	ds_read_b64 v[10:11], v232 offset:12288
	ds_read_b64 v[12:13], v233 offset:12288
	v_exp_f32_e32 v90, v90
	v_exp_f32_e32 v91, v91
	v_add_f32_e32 v0, v88, v0
	v_add_f32_e32 v0, v89, v0
	s_waitcnt lgkmcnt(8)
	v_mfma_f32_32x32x16_bf16 v[48:63], v[242:245], v[2:5], v[48:63]
	ds_read_b64 v[242:243], v232 offset:16384
	ds_read_b64 v[244:245], v233 offset:16384
	v_exp_f32_e32 v92, v92
	v_exp_f32_e32 v93, v93
	v_add_f32_e32 v0, v90, v0
	v_add_f32_e32 v0, v91, v0
	s_waitcnt lgkmcnt(8)
	v_mfma_f32_32x32x16_bf16 v[32:47], v[80:83], v[2:5], v[32:47]
	ds_read_b64 v[80:81], v234 offset:8192
	ds_read_b64 v[82:83], v235 offset:8192
	v_exp_f32_e32 v94, v94
	v_exp_f32_e32 v95, v95
	v_add_f32_e32 v0, v92, v0
	v_add_f32_e32 v0, v93, v0
	v_add_f32_e32 v0, v94, v0
	v_add_f32_e32 v0, v95, v0
	v_cvt_pk_bf16_f32 v2, v88, v89
	v_cvt_pk_bf16_f32 v3, v90, v91
	v_cvt_pk_bf16_f32 v4, v92, v93
	v_cvt_pk_bf16_f32 v5, v94, v95
	s_nop 1
	ds_read_b64 v[88:89], v236 offset:20480
	ds_read_b64 v[90:91], v237 offset:20480
	s_waitcnt lgkmcnt(10)
	v_mfma_f32_32x32x16_bf16 v[64:79], v[84:87], v[2:5], v[64:79]
	ds_read_b64 v[92:93], v236 offset:12288
	ds_read_b64 v[94:95], v237 offset:12288
	v_exp_f32_e32 v96, v96
	v_exp_f32_e32 v97, v97
	s_waitcnt lgkmcnt(10)
	v_mfma_f32_32x32x16_bf16 v[112:127], v[6:9], v[2:5], v[112:127]
	ds_read_b64 v[84:85], v236 offset:16384
	ds_read_b64 v[86:87], v237 offset:16384
	v_exp_f32_e32 v98, v98
	v_exp_f32_e32 v99, v99
	v_add_f32_e32 v0, v96, v0
	v_add_f32_e32 v0, v97, v0
	s_waitcnt lgkmcnt(10)
	v_mfma_f32_32x32x16_bf16 v[48:63], v[10:13], v[2:5], v[48:63]
	ds_read_b64 v[6:7], v238 offset:8192
	ds_read_b64 v[8:9], v239 offset:8192
	v_exp_f32_e32 v100, v100
	v_exp_f32_e32 v101, v101
	v_add_f32_e32 v0, v98, v0
	v_add_f32_e32 v0, v99, v0
	s_waitcnt lgkmcnt(10)
	v_mfma_f32_32x32x16_bf16 v[32:47], v[242:245], v[2:5], v[32:47]
	ds_read_b64 v[10:11], v240 offset:12288
	ds_read_b64 v[12:13], v241 offset:12288
	v_exp_f32_e32 v102, v102
	v_exp_f32_e32 v103, v103
	v_add_f32_e32 v0, v100, v0
	v_add_f32_e32 v0, v101, v0
	v_add_f32_e32 v0, v102, v0
	v_add_f32_e32 v0, v103, v0
	v_cvt_pk_bf16_f32 v2, v96, v97
	v_cvt_pk_bf16_f32 v3, v98, v99
	v_cvt_pk_bf16_f32 v4, v100, v101
	v_cvt_pk_bf16_f32 v5, v102, v103
	s_nop 1
	ds_read_b64 v[242:243], v240 offset:16384
	ds_read_b64 v[244:245], v241 offset:16384
	s_waitcnt lgkmcnt(12)
	v_mfma_f32_32x32x16_bf16 v[64:79], v[80:83], v[2:5], v[64:79]
	ds_read_b64 v[96:97], v240 offset:20480
	ds_read_b64 v[98:99], v241 offset:20480
	v_exp_f32_e32 v104, v104
	v_exp_f32_e32 v105, v105
	s_waitcnt lgkmcnt(12)
	v_mfma_f32_32x32x16_bf16 v[112:127], v[88:91], v[2:5], v[112:127]
	v_exp_f32_e32 v106, v106
	v_exp_f32_e32 v107, v107
	v_add_f32_e32 v0, v104, v0
	v_add_f32_e32 v0, v105, v0
	s_waitcnt lgkmcnt(10)
	v_mfma_f32_32x32x16_bf16 v[48:63], v[92:95], v[2:5], v[48:63]
	v_exp_f32_e32 v108, v108
	v_exp_f32_e32 v109, v109
	v_add_f32_e32 v0, v106, v0
	v_add_f32_e32 v0, v107, v0
	s_waitcnt lgkmcnt(8)
	v_mfma_f32_32x32x16_bf16 v[32:47], v[84:87], v[2:5], v[32:47]
	v_exp_f32_e32 v110, v110
	v_exp_f32_e32 v111, v111
	v_add_f32_e32 v0, v108, v0
	v_add_f32_e32 v0, v109, v0
	v_add_f32_e32 v0, v110, v0
	v_add_f32_e32 v0, v111, v0
	v_cvt_pk_bf16_f32 v2, v104, v105
	v_cvt_pk_bf16_f32 v3, v106, v107
	v_cvt_pk_bf16_f32 v4, v108, v109
	v_cvt_pk_bf16_f32 v5, v110, v111
	s_nop 1
	s_waitcnt lgkmcnt(6)
	v_mfma_f32_32x32x16_bf16 v[64:79], v[6:9], v[2:5], v[64:79]
	s_waitcnt lgkmcnt(4)
	v_mfma_f32_32x32x16_bf16 v[48:63], v[10:13], v[2:5], v[48:63]
	s_waitcnt lgkmcnt(2)
	v_mfma_f32_32x32x16_bf16 v[32:47], v[242:245], v[2:5], v[32:47]
	s_waitcnt lgkmcnt(0)
	v_mfma_f32_32x32x16_bf16 v[112:127], v[96:99], v[2:5], v[112:127]
	v_add_f32_e32 v224, v224, v0

.LBB0_1427:
	ds_read_b64 v[6:7], v226 offset:32768
	ds_read_b64 v[8:9], v227 offset:32768
	ds_read_b64 v[10:11], v228 offset:45056
	ds_read_b64 v[12:13], v229 offset:45056
	ds_read_b64 v[242:243], v228 offset:36864
	ds_read_b64 v[244:245], v229 offset:36864
	v_exp_f32_e32 v128, v128
	v_exp_f32_e32 v129, v129
	v_exp_f32_e32 v130, v130
	v_exp_f32_e32 v131, v131
	v_exp_f32_e32 v132, v132
	v_exp_f32_e32 v133, v133
	v_exp_f32_e32 v134, v134
	v_exp_f32_e32 v135, v135
	v_cvt_pk_bf16_f32 v2, v128, v129
	v_cvt_pk_bf16_f32 v3, v130, v131
	v_cvt_pk_bf16_f32 v4, v132, v133
	v_cvt_pk_bf16_f32 v5, v134, v135
	v_add_f32_e32 v0, 0, v128
	v_add_f32_e32 v0, v129, v0
	v_add_f32_e32 v0, v130, v0
	v_add_f32_e32 v0, v131, v0
	v_add_f32_e32 v0, v132, v0
	v_add_f32_e32 v0, v133, v0
	v_add_f32_e32 v0, v134, v0
	v_add_f32_e32 v0, v135, v0
	ds_read_b64 v[128:129], v228 offset:40960
	ds_read_b64 v[130:131], v229 offset:40960
	ds_read_b64 v[132:133], v230 offset:32768
	ds_read_b64 v[134:135], v231 offset:32768
	s_waitcnt lgkmcnt(8)
	v_mfma_f32_32x32x16_bf16 v[64:79], v[6:9], v[2:5], v[64:79]
	ds_read_b64 v[6:7], v232 offset:45056
	ds_read_b64 v[8:9], v233 offset:45056
	v_exp_f32_e32 v136, v136
	v_exp_f32_e32 v137, v137
	s_waitcnt lgkmcnt(8)
	v_mfma_f32_32x32x16_bf16 v[112:127], v[10:13], v[2:5], v[112:127]
	ds_read_b64 v[10:11], v232 offset:36864
	ds_read_b64 v[12:13], v233 offset:36864
	v_exp_f32_e32 v138, v138
	v_exp_f32_e32 v139, v139
	v_add_f32_e32 v0, v136, v0
	v_add_f32_e32 v0, v137, v0
	s_waitcnt lgkmcnt(8)
	v_mfma_f32_32x32x16_bf16 v[48:63], v[242:245], v[2:5], v[48:63]
	ds_read_b64 v[242:243], v232 offset:40960
	ds_read_b64 v[244:245], v233 offset:40960
	v_exp_f32_e32 v140, v140
	v_exp_f32_e32 v141, v141
	v_add_f32_e32 v0, v138, v0
	v_add_f32_e32 v0, v139, v0
	s_waitcnt lgkmcnt(8)
	v_mfma_f32_32x32x16_bf16 v[32:47], v[128:131], v[2:5], v[32:47]
	ds_read_b64 v[128:129], v234 offset:32768
	ds_read_b64 v[130:131], v235 offset:32768
	v_exp_f32_e32 v142, v142
	v_exp_f32_e32 v143, v143
	v_add_f32_e32 v0, v140, v0
	v_add_f32_e32 v0, v141, v0
	v_add_f32_e32 v0, v142, v0
	v_add_f32_e32 v0, v143, v0
	v_cvt_pk_bf16_f32 v2, v136, v137
	v_cvt_pk_bf16_f32 v3, v138, v139
	v_cvt_pk_bf16_f32 v4, v140, v141
	v_cvt_pk_bf16_f32 v5, v142, v143
	s_nop 1
	ds_read_b64 v[136:137], v236 offset:45056
	ds_read_b64 v[138:139], v237 offset:45056
	s_waitcnt lgkmcnt(10)
	v_mfma_f32_32x32x16_bf16 v[64:79], v[132:135], v[2:5], v[64:79]
	ds_read_b64 v[140:141], v236 offset:36864
	ds_read_b64 v[142:143], v237 offset:36864
	v_exp_f32_e32 v144, v144
	v_exp_f32_e32 v145, v145
	s_waitcnt lgkmcnt(10)
	v_mfma_f32_32x32x16_bf16 v[112:127], v[6:9], v[2:5], v[112:127]
	ds_read_b64 v[132:133], v236 offset:40960
	ds_read_b64 v[134:135], v237 offset:40960
	v_exp_f32_e32 v146, v146
	v_exp_f32_e32 v147, v147
	v_add_f32_e32 v0, v144, v0
	v_add_f32_e32 v0, v145, v0
	s_waitcnt lgkmcnt(10)
	v_mfma_f32_32x32x16_bf16 v[48:63], v[10:13], v[2:5], v[48:63]
	ds_read_b64 v[6:7], v238 offset:32768
	ds_read_b64 v[8:9], v239 offset:32768
	v_exp_f32_e32 v148, v148
	v_exp_f32_e32 v149, v149
	v_add_f32_e32 v0, v146, v0
	v_add_f32_e32 v0, v147, v0
	s_waitcnt lgkmcnt(10)
	v_mfma_f32_32x32x16_bf16 v[32:47], v[242:245], v[2:5], v[32:47]
	ds_read_b64 v[10:11], v240 offset:36864
	ds_read_b64 v[12:13], v241 offset:36864
	v_exp_f32_e32 v150, v150
	v_exp_f32_e32 v151, v151
	v_add_f32_e32 v0, v148, v0
	v_add_f32_e32 v0, v149, v0
	v_add_f32_e32 v0, v150, v0
	v_add_f32_e32 v0, v151, v0
	v_cvt_pk_bf16_f32 v2, v144, v145
	v_cvt_pk_bf16_f32 v3, v146, v147
	v_cvt_pk_bf16_f32 v4, v148, v149
	v_cvt_pk_bf16_f32 v5, v150, v151
	s_nop 1
	ds_read_b64 v[242:243], v240 offset:40960
	ds_read_b64 v[244:245], v241 offset:40960
	s_waitcnt lgkmcnt(12)
	v_mfma_f32_32x32x16_bf16 v[64:79], v[128:131], v[2:5], v[64:79]
	ds_read_b64 v[144:145], v240 offset:45056
	ds_read_b64 v[146:147], v241 offset:45056
	v_exp_f32_e32 v152, v152
	v_exp_f32_e32 v153, v153
	s_waitcnt lgkmcnt(12)
	v_mfma_f32_32x32x16_bf16 v[112:127], v[136:139], v[2:5], v[112:127]
	v_exp_f32_e32 v154, v154
	v_exp_f32_e32 v155, v155
	v_add_f32_e32 v0, v152, v0
	v_add_f32_e32 v0, v153, v0
	s_waitcnt lgkmcnt(10)
	v_mfma_f32_32x32x16_bf16 v[48:63], v[140:143], v[2:5], v[48:63]
	v_exp_f32_e32 v156, v156
	v_exp_f32_e32 v157, v157
	v_add_f32_e32 v0, v154, v0
	v_add_f32_e32 v0, v155, v0
	s_waitcnt lgkmcnt(8)
	v_mfma_f32_32x32x16_bf16 v[32:47], v[132:135], v[2:5], v[32:47]
	v_exp_f32_e32 v158, v158
	v_exp_f32_e32 v159, v159
	v_add_f32_e32 v0, v156, v0
	v_add_f32_e32 v0, v157, v0
	v_add_f32_e32 v0, v158, v0
	v_add_f32_e32 v0, v159, v0
	v_cvt_pk_bf16_f32 v2, v152, v153
	v_cvt_pk_bf16_f32 v3, v154, v155
	v_cvt_pk_bf16_f32 v4, v156, v157
	v_cvt_pk_bf16_f32 v5, v158, v159
	s_nop 1
	s_waitcnt lgkmcnt(6)
	v_mfma_f32_32x32x16_bf16 v[64:79], v[6:9], v[2:5], v[64:79]
	s_waitcnt lgkmcnt(4)
	v_mfma_f32_32x32x16_bf16 v[48:63], v[10:13], v[2:5], v[48:63]
	s_waitcnt lgkmcnt(2)
	v_mfma_f32_32x32x16_bf16 v[32:47], v[242:245], v[2:5], v[32:47]
	s_waitcnt lgkmcnt(0)
	v_mfma_f32_32x32x16_bf16 v[112:127], v[144:147], v[2:5], v[112:127]
	v_add_f32_e32 v224, v0, v224
